# cache policy: read-back loads of the private branch / gated-sum tiles in the P8 gate epilogue also non-temporal
# baseline (speedup 1.0000x reference)
.LBB0_1127:
	v_ashrrev_i32_e32 v207, 31, v206
	v_lshl_add_u64 v[130:131], v[206:207], 2, s[24:25]
	global_load_dword v218, v[130:131], off
	global_load_dwordx4 v[190:193], v[198:199], off nt
	s_cmp_gt_i32 s72, 0
	s_cselect_b64 s[12:13], -1, 0
	s_cmp_lt_i32 s72, 1
	v_lshl_add_u64 v[216:217], v[204:205], 4, s[18:19]
	s_cbranch_scc1 .LBB0_1129
	global_load_dwordx4 v[186:189], v[216:217], off nt
	s_branch .LBB0_1130

.LBB0_1130:
	global_load_dwordx4 v[182:185], v[198:199], off offset:1024 nt
	v_cndmask_b32_e64 v130, 0, 1, s[12:13]
	v_mov_b32_e32 v172, 0
	v_cmp_ne_u32_e64 s[8:9], 1, v130
	s_andn2_b64 vcc, exec, s[12:13]
	v_mov_b32_e32 v180, 0
	v_mov_b32_e32 v181, 0
	v_mov_b32_e32 v178, 0
	v_mov_b32_e32 v179, 0
	s_cbranch_vccnz .LBB0_1132
	global_load_dwordx4 v[178:181], v[216:217], off offset:1024 nt
.LBB0_1132:
	v_add_u32_e32 v130, 16, v206
	v_ashrrev_i32_e32 v131, 31, v130
	v_lshl_add_u64 v[130:131], v[130:131], 2, s[24:25]
	global_load_dword v229, v[130:131], off
	global_load_dwordx4 v[174:177], v[198:199], off offset:2048 nt
	s_and_b64 vcc, exec, s[8:9]
	v_mov_b32_e32 v173, 0
	v_mov_b32_e32 v170, 0
	v_mov_b32_e32 v171, 0
	s_cbranch_vccnz .LBB0_1134
	global_load_dwordx4 v[170:173], v[216:217], off offset:2048 nt
.LBB0_1134:
	global_load_dwordx4 v[166:169], v[198:199], off offset:3072 nt
	v_mov_b32_e32 v156, 0
	s_and_b64 vcc, exec, s[8:9]
	v_mov_b32_e32 v164, 0
	v_mov_b32_e32 v165, 0
	v_mov_b32_e32 v162, 0
	v_mov_b32_e32 v163, 0
	s_cbranch_vccnz .LBB0_1136
	global_load_dwordx4 v[162:165], v[216:217], off offset:3072 nt
.LBB0_1136:
	v_add_u32_e32 v130, 32, v206
	v_ashrrev_i32_e32 v131, 31, v130
	v_lshl_add_u64 v[130:131], v[130:131], 2, s[24:25]
	v_add_co_u32_e32 v132, vcc, 0x1000, v198
	v_mov_b32_e32 v157, 0
	s_nop 0
	v_addc_co_u32_e32 v133, vcc, 0, v199, vcc
	global_load_dword v207, v[130:131], off
	global_load_dwordx4 v[158:161], v[132:133], off nt
	v_add_u32_e32 v130, 0x100, v204
	v_ashrrev_i32_e32 v131, 31, v130
	s_and_b64 vcc, exec, s[8:9]
	v_lshl_add_u64 v[214:215], v[130:131], 4, s[18:19]
	v_mov_b32_e32 v154, 0
	v_mov_b32_e32 v155, 0
	s_cbranch_vccnz .LBB0_1138
	global_load_dwordx4 v[154:157], v[214:215], off nt
.LBB0_1138:
	v_add_co_u32_e32 v130, vcc, 0x1000, v198
	v_mov_b32_e32 v140, 0
	s_nop 0
	v_addc_co_u32_e32 v131, vcc, 0, v199, vcc
	global_load_dwordx4 v[150:153], v[130:131], off offset:1024 nt
	v_add_u32_e32 v130, 0x140, v204
	v_ashrrev_i32_e32 v131, 31, v130
	s_and_b64 vcc, exec, s[8:9]
	v_lshl_add_u64 v[212:213], v[130:131], 4, s[18:19]
	v_mov_b32_e32 v148, 0
	v_mov_b32_e32 v149, 0
	v_mov_b32_e32 v146, 0
	v_mov_b32_e32 v147, 0
	s_cbranch_vccnz .LBB0_1140
	global_load_dwordx4 v[146:149], v[212:213], off nt
.LBB0_1140:
	v_add_u32_e32 v130, 48, v206
	v_ashrrev_i32_e32 v131, 31, v130
	v_lshl_add_u64 v[130:131], v[130:131], 2, s[24:25]
	v_add_co_u32_e32 v132, vcc, 0x1000, v198
	v_mov_b32_e32 v141, 0
	s_nop 0
	v_addc_co_u32_e32 v133, vcc, 0, v199, vcc
	global_load_dword v205, v[130:131], off
	global_load_dwordx4 v[142:145], v[132:133], off offset:2048 nt
	v_add_u32_e32 v130, 0x180, v204
	v_ashrrev_i32_e32 v131, 31, v130
	s_and_b64 vcc, exec, s[8:9]
	v_lshl_add_u64 v[210:211], v[130:131], 4, s[18:19]
	v_mov_b32_e32 v138, 0
	v_mov_b32_e32 v139, 0
	s_cbranch_vccnz .LBB0_1142
	global_load_dwordx4 v[138:141], v[210:211], off nt
.LBB0_1142:
	v_add_co_u32_e32 v130, vcc, 0x1000, v198
	s_nop 1
	v_addc_co_u32_e32 v131, vcc, 0, v199, vcc
	global_load_dwordx4 v[134:137], v[130:131], off offset:3072 nt
	v_add_u32_e32 v130, 0x1c0, v204
	v_ashrrev_i32_e32 v131, 31, v130
	s_and_b64 vcc, exec, s[8:9]
	v_lshl_add_u64 v[208:209], v[130:131], 4, s[18:19]
	s_cbranch_vccnz .LBB0_1144
	global_load_dwordx4 v[130:133], v[208:209], off nt
	s_branch .LBB0_1145

.LBB0_1179:
	v_add_u32_e32 v66, 0x80, v206
	v_ashrrev_i32_e32 v67, 31, v66
	v_add_u32_e32 v70, 0x200, v204
	v_lshl_add_u64 v[68:69], v[66:67], 2, s[24:25]
	v_ashrrev_i32_e32 v71, 31, v70
	v_lshl_add_u64 v[72:73], v[70:71], 4, s[10:11]
	global_load_dword v142, v[68:69], off
	global_load_dwordx4 v[126:129], v[72:73], off nt
	s_cmp_gt_i32 s72, 0
	s_cselect_b64 s[12:13], -1, 0
	s_cmp_lt_i32 s72, 1
	v_lshl_add_u64 v[146:147], v[70:71], 4, s[18:19]
	s_cbranch_scc1 .LBB0_1181
	global_load_dwordx4 v[122:125], v[146:147], off nt
	s_branch .LBB0_1182

.LBB0_1182:
	v_add_u32_e32 v68, 0x240, v204
	v_ashrrev_i32_e32 v69, 31, v68
	v_lshl_add_u64 v[70:71], v[68:69], 4, s[10:11]
	global_load_dwordx4 v[118:121], v[70:71], off nt
	v_cndmask_b32_e64 v67, 0, 1, s[12:13]
	v_mov_b32_e32 v108, 0
	v_cmp_ne_u32_e64 s[8:9], 1, v67
	s_andn2_b64 vcc, exec, s[12:13]
	v_lshl_add_u64 v[144:145], v[68:69], 4, s[18:19]
	v_mov_b32_e32 v116, 0
	v_mov_b32_e32 v117, 0
	v_mov_b32_e32 v114, 0
	v_mov_b32_e32 v115, 0
	s_cbranch_vccnz .LBB0_1184
	global_load_dwordx4 v[114:117], v[144:145], off nt
.LBB0_1184:
	v_add_u32_e32 v68, 16, v66
	v_ashrrev_i32_e32 v69, 31, v68
	v_add_u32_e32 v70, 0x280, v204
	v_lshl_add_u64 v[68:69], v[68:69], 2, s[24:25]
	v_ashrrev_i32_e32 v71, 31, v70
	v_lshl_add_u64 v[72:73], v[70:71], 4, s[10:11]
	global_load_dword v150, v[68:69], off
	global_load_dwordx4 v[110:113], v[72:73], off nt
	s_and_b64 vcc, exec, s[8:9]
	v_lshl_add_u64 v[140:141], v[70:71], 4, s[18:19]
	v_mov_b32_e32 v109, 0
	v_mov_b32_e32 v106, 0
	v_mov_b32_e32 v107, 0
	s_cbranch_vccnz .LBB0_1186
	global_load_dwordx4 v[106:109], v[140:141], off nt
.LBB0_1186:
	v_add_u32_e32 v68, 0x2c0, v204
	v_ashrrev_i32_e32 v69, 31, v68
	v_lshl_add_u64 v[70:71], v[68:69], 4, s[10:11]
	global_load_dwordx4 v[102:105], v[70:71], off nt
	v_mov_b32_e32 v92, 0
	s_and_b64 vcc, exec, s[8:9]
	v_lshl_add_u64 v[138:139], v[68:69], 4, s[18:19]
	v_mov_b32_e32 v100, 0
	v_mov_b32_e32 v101, 0
	v_mov_b32_e32 v98, 0
	v_mov_b32_e32 v99, 0
	s_cbranch_vccnz .LBB0_1188
	global_load_dwordx4 v[98:101], v[138:139], off nt
.LBB0_1188:
	v_add_u32_e32 v68, 32, v66
	v_ashrrev_i32_e32 v69, 31, v68
	v_add_u32_e32 v70, 0x300, v204
	v_lshl_add_u64 v[68:69], v[68:69], 2, s[24:25]
	v_ashrrev_i32_e32 v71, 31, v70
	v_lshl_add_u64 v[72:73], v[70:71], 4, s[10:11]
	global_load_dword v149, v[68:69], off
	global_load_dwordx4 v[94:97], v[72:73], off nt
	s_and_b64 vcc, exec, s[8:9]
	v_lshl_add_u64 v[136:137], v[70:71], 4, s[18:19]
	v_mov_b32_e32 v93, 0
	v_mov_b32_e32 v90, 0
	v_mov_b32_e32 v91, 0
	s_cbranch_vccnz .LBB0_1190
	global_load_dwordx4 v[90:93], v[136:137], off nt
.LBB0_1190:
	v_add_u32_e32 v68, 0x340, v204
	v_ashrrev_i32_e32 v69, 31, v68
	v_lshl_add_u64 v[70:71], v[68:69], 4, s[10:11]
	global_load_dwordx4 v[86:89], v[70:71], off nt
	v_mov_b32_e32 v76, 0
	s_and_b64 vcc, exec, s[8:9]
	v_lshl_add_u64 v[134:135], v[68:69], 4, s[18:19]
	v_mov_b32_e32 v84, 0
	v_mov_b32_e32 v85, 0
	v_mov_b32_e32 v82, 0
	v_mov_b32_e32 v83, 0
	s_cbranch_vccnz .LBB0_1192
	global_load_dwordx4 v[82:85], v[134:135], off nt
.LBB0_1192:
	v_add_u32_e32 v66, 48, v66
	v_ashrrev_i32_e32 v67, 31, v66
	v_add_u32_e32 v68, 0x380, v204
	v_lshl_add_u64 v[66:67], v[66:67], 2, s[24:25]
	v_ashrrev_i32_e32 v69, 31, v68
	v_lshl_add_u64 v[70:71], v[68:69], 4, s[10:11]
	global_load_dword v148, v[66:67], off
	global_load_dwordx4 v[78:81], v[70:71], off nt
	s_and_b64 vcc, exec, s[8:9]
	v_lshl_add_u64 v[132:133], v[68:69], 4, s[18:19]
	v_mov_b32_e32 v77, 0
	v_mov_b32_e32 v74, 0
	v_mov_b32_e32 v75, 0
	s_cbranch_vccnz .LBB0_1194
	global_load_dwordx4 v[74:77], v[132:133], off nt
.LBB0_1194:
	v_add_u32_e32 v66, 0x3c0, v204
	v_ashrrev_i32_e32 v67, 31, v66
	v_lshl_add_u64 v[68:69], v[66:67], 4, s[10:11]
	global_load_dwordx4 v[70:73], v[68:69], off nt
	s_and_b64 vcc, exec, s[8:9]
	v_lshl_add_u64 v[130:131], v[66:67], 4, s[18:19]
	s_cbranch_vccnz .LBB0_1196
	global_load_dwordx4 v[66:69], v[130:131], off nt
	s_branch .LBB0_1197
